# EpiGate: conv-weight/bias vector loads issued at the start of the epilogue; NA row-0 Q prefetched during window staging
# speedup vs baseline: 1.0263x; 1.0027x over previous
.LBB0_118:
	s_ashr_i32 s2, s63, 6
	s_ashr_i32 s56, s63, 2
	s_ashr_i32 s3, s2, 31
	s_and_b32 s58, s56, 15
	s_lshl_b64 s[2:3], s[2:3], 10
	s_add_u32 s2, s2, 0x2000
	s_addc_u32 s3, s3, 0
	s_lshl_b64 s[20:21], s[2:3], 11
	v_readlane_b32 s22, v253, 4
	v_readlane_b32 s23, v253, 5
	s_add_u32 s20, s22, s20
	s_addc_u32 s21, s23, s21
	s_lshl_b32 s26, s58, 7
	s_add_u32 s34, s20, s26
	s_addc_u32 s35, s21, 0
	s_lshl_b32 s20, s63, 2
	s_and_b32 s22, s20, 12
	v_sub_u32_e64 v0, s22, 4 clamp
	v_lshlrev_b32_e32 v1, 6, v0
	v_add_u32_e32 v2, v1, v108
	v_ashrrev_i32_e32 v3, 31, v2
	v_lshl_add_u64 v[70:71], s[34:35], 0, v[178:179]
	v_lshlrev_b64 v[2:3], 11, v[2:3]
	v_lshl_add_u64 v[2:3], v[70:71], 0, v[2:3]
	s_barrier
	global_load_dwordx4 v[12:15], v[2:3], off
	v_and_b32_e32 v1, 0x100, v1
	s_ashr_i32 s57, s56, 31
	v_add_u32_e32 v6, v1, v108
	s_movk_i32 s59, 0x90
	s_lshl_b64 s[36:37], s[56:57], 17
	v_mad_u64_u32 v[80:81], s[34:35], v6, s59, v[110:111]
	v_lshl_add_u64 v[68:69], v[138:139], 0, s[36:37]
	s_max_u32 s21, s22, 4
	s_lshl_b32 s20, s21, 6
	v_lshl_add_u32 v146, v1, 1, v109
	s_add_i32 s34, s20, 0xffffff40
	s_and_b32 s23, s34, 0x140
	s_mov_b32 s35, s27
	v_mov_b32_e32 v145, s3
	v_lshl_add_u64 v[142:143], v[112:113], 0, s[26:27]
	v_lshl_or_b32 v246, s22, 6, v111
	v_or_b32_e32 v144, s2, v246
	v_lshlrev_b64 v[140:141], 11, v[144:145]
	v_lshl_add_u64 v[88:89], v[142:143], 0, v[140:141]
	global_load_dwordx4 v[238:241], v[88:89], off
	global_load_dwordx4 v[242:245], v[88:89], off offset:64
	s_mov_b64 s[0:1], s[90:91]
	v_readlane_b32 s80, v253, 46
	v_readlane_b32 s94, v253, 60
	v_readlane_b32 s95, v253, 61
	v_lshlrev_b32_e32 v97, 2, v122
	v_lshlrev_b32_e32 v95, 2, v126
	v_lshlrev_b32_e32 v93, 2, v124
	v_lshlrev_b32_e32 v98, 2, v118
	v_lshlrev_b32_e32 v92, 2, v128
	v_lshlrev_b32_e32 v99, 2, v114
	v_lshlrev_b32_e32 v96, 2, v116
	v_lshlrev_b32_e32 v94, 2, v120
	v_readlane_b32 s81, v253, 47
	v_readlane_b32 s82, v253, 48
	v_readlane_b32 s83, v253, 49
	v_readlane_b32 s84, v253, 50
	v_readlane_b32 s85, v253, 51
	v_readlane_b32 s86, v253, 52
	v_readlane_b32 s87, v253, 53
	v_readlane_b32 s88, v253, 54
	v_readlane_b32 s89, v253, 55
	v_readlane_b32 s90, v253, 56
	v_readlane_b32 s91, v253, 57
	v_readlane_b32 s92, v253, 58
	v_readlane_b32 s93, v253, 59
	v_lshlrev_b32_e32 v2, 7, v0
	v_mov_b32_e32 v3, v179
	v_lshl_add_u64 v[2:3], v[68:69], 0, v[2:3]
	global_load_dwordx4 v[16:19], v[2:3], off
	v_add_u32_e32 v2, s34, v108
	v_ashrrev_i32_e32 v3, 31, v2
	v_lshlrev_b64 v[2:3], 11, v[2:3]
	v_lshl_add_u64 v[2:3], v[70:71], 0, v[2:3]
	global_load_dwordx4 v[20:23], v[2:3], off
	v_add_u32_e32 v1, s23, v108
	v_mad_u64_u32 v[82:83], s[36:37], v1, s59, v[110:111]
	v_lshl_add_u32 v147, s23, 1, v109
	v_lshl_add_u64 v[2:3], s[34:35], 1, v[68:69]
	global_load_dwordx4 v[24:27], v[2:3], off
	s_add_i32 s34, s20, 0xffffff80
	s_and_b32 s23, s34, 0x180
	v_add_u32_e32 v2, s34, v108
	v_ashrrev_i32_e32 v3, 31, v2
	v_lshlrev_b64 v[2:3], 11, v[2:3]
	v_lshl_add_u64 v[2:3], v[70:71], 0, v[2:3]
	global_load_dwordx4 v[28:31], v[2:3], off
	v_add_u32_e32 v1, s23, v108
	v_mad_u64_u32 v[84:85], s[36:37], v1, s59, v[110:111]
	v_lshl_add_u32 v148, s23, 1, v109
	v_lshl_add_u64 v[2:3], s[34:35], 1, v[68:69]
	global_load_dwordx4 v[32:35], v[2:3], off
	s_sub_i32 s34, s20, 64
	s_and_b32 s23, s34, 0x1c0
	v_add_u32_e32 v2, s34, v108
	v_ashrrev_i32_e32 v3, 31, v2
	v_lshlrev_b64 v[2:3], 11, v[2:3]
	v_lshl_add_u64 v[2:3], v[70:71], 0, v[2:3]
	global_load_dwordx4 v[36:39], v[2:3], off
	v_add_u32_e32 v1, s23, v108
	v_mad_u64_u32 v[86:87], s[36:37], v1, s59, v[110:111]
	v_lshl_add_u32 v149, s23, 1, v109
	s_and_b32 s23, s20, 0x100
	v_lshl_add_u64 v[2:3], s[34:35], 1, v[68:69]
	global_load_dwordx4 v[40:43], v[2:3], off
	v_add_u32_e32 v2, s20, v108
	v_ashrrev_i32_e32 v3, 31, v2
	v_lshlrev_b64 v[2:3], 11, v[2:3]
	v_lshl_add_u64 v[2:3], v[70:71], 0, v[2:3]
	global_load_dwordx4 v[44:47], v[2:3], off
	v_add_u32_e32 v1, s23, v108
	v_mad_u64_u32 v[100:101], s[34:35], v1, s59, v[110:111]
	s_lshl_b32 s34, s21, 7
	s_mov_b32 s35, s27
	v_lshl_add_u32 v150, s23, 1, v109
	s_or_b32 s21, s20, 64
	v_lshl_add_u64 v[6:7], v[68:69], 0, s[34:35]
	global_load_dwordx4 v[48:51], v[6:7], off
	v_add_u32_e32 v2, s21, v108
	v_ashrrev_i32_e32 v3, 31, v2
	v_lshlrev_b64 v[2:3], 11, v[2:3]
	v_lshl_add_u64 v[2:3], v[70:71], 0, v[2:3]
	global_load_dwordx4 v[52:55], v[2:3], off
	s_and_b32 s21, s21, 0x140
	v_add_u32_e32 v1, s21, v108
	v_mad_u64_u32 v[102:103], s[34:35], v1, s59, v[110:111]
	v_lshl_add_u32 v151, s21, 1, v109
	s_or_b32 s21, s20, 0x80
	s_or_b32 s20, s20, 0xc0
	global_load_dwordx4 v[56:59], v[6:7], off offset:128
	v_add_u32_e32 v2, s21, v108
	v_ashrrev_i32_e32 v3, 31, v2
	v_lshlrev_b64 v[2:3], 11, v[2:3]
	v_lshl_add_u64 v[2:3], v[70:71], 0, v[2:3]
	global_load_dwordx4 v[60:63], v[2:3], off
	s_and_b32 s21, s21, 0x180
	v_add_u32_e32 v1, s21, v108
	v_mad_u64_u32 v[104:105], s[34:35], v1, s59, v[110:111]
	v_lshl_add_u32 v152, s21, 1, v109
	global_load_dwordx4 v[64:67], v[6:7], off offset:256
	v_add_u32_e32 v2, s20, v108
	v_ashrrev_i32_e32 v3, 31, v2
	v_lshlrev_b64 v[2:3], 11, v[2:3]
	v_lshl_add_u64 v[2:3], v[70:71], 0, v[2:3]
	global_load_dwordx4 v[72:75], v[2:3], off
	s_and_b32 s20, s20, 0x1c0
	v_add_u32_e32 v1, s20, v108
	v_mad_u64_u32 v[106:107], s[34:35], v1, s59, v[110:111]
	v_lshl_add_u32 v153, s20, 1, v109
	s_mul_i32 s20, s58, 0x744
	s_add_u32 s36, s94, s20
	v_readfirstlane_b32 s20, v0
	s_addc_u32 s23, s95, 0
	s_add_i32 s20, s20, s61
	s_sub_i32 s21, s20, s22
	s_lshl_b32 s20, s20, 6
	s_and_b32 s35, s20, 0x100
	v_or_b32_e32 v0, s35, v115
	s_or_b32 s34, s35, 64
	s_or_b32 s33, s35, 0x80
	s_or_b32 s26, s35, 0xc0
	s_mul_i32 s20, s21, 31
	s_ashr_i32 s21, s20, 31
	s_lshl_b64 s[20:21], s[20:21], 2
	s_add_u32 s20, s36, s20
	s_addc_u32 s21, s23, s21
	global_load_dwordx4 v[76:79], v[6:7], off offset:384
	s_waitcnt vmcnt(15)
	ds_write_b128 v80, v[12:15]
	s_waitcnt vmcnt(14)
	ds_write_b128 v146, v[16:19]
	s_waitcnt vmcnt(13)
	ds_write_b128 v82, v[20:23]
	s_waitcnt vmcnt(12)
	ds_write_b128 v147, v[24:27]
	s_waitcnt vmcnt(11)
	ds_write_b128 v84, v[28:31]
	s_waitcnt vmcnt(10)
	ds_write_b128 v148, v[32:35]
	s_waitcnt vmcnt(9)
	ds_write_b128 v86, v[36:39]
	s_waitcnt vmcnt(8)
	ds_write_b128 v149, v[40:43]
	s_waitcnt vmcnt(7)
	ds_write_b128 v100, v[44:47]
	s_waitcnt vmcnt(6)
	ds_write_b128 v150, v[48:51]
	s_waitcnt vmcnt(5)
	ds_write_b128 v102, v[52:55]
	s_waitcnt vmcnt(4)
	ds_write_b128 v151, v[56:59]
	s_waitcnt vmcnt(3)
	ds_write_b128 v104, v[60:63]
	s_waitcnt vmcnt(2)
	ds_write_b128 v152, v[64:67]
	s_waitcnt vmcnt(1)
	ds_write_b128 v106, v[72:75]
	s_waitcnt vmcnt(0)
	ds_write_b128 v153, v[76:79]
	s_waitcnt lgkmcnt(0)
	s_barrier
	v_mov_b64_e32 v[20:21], v[238:239]
	v_mov_b64_e32 v[22:23], v[240:241]
	v_mov_b64_e32 v[24:25], v[242:243]
	v_mov_b64_e32 v[26:27], v[244:245]
	global_load_dword v194, v98, s[20:21] offset:868
	global_load_dword v195, v99, s[20:21] offset:868
	global_load_dword v196, v97, s[20:21] offset:868
	global_load_dword v197, v95, s[20:21] offset:868
	global_load_dword v198, v93, s[20:21] offset:868
	global_load_dword v199, v96, s[20:21] offset:868
	global_load_dword v200, v97, s[20:21] offset:992
	global_load_dword v201, v93, s[20:21] offset:992
	global_load_dword v202, v92, s[20:21] offset:868
	global_load_dword v203, v95, s[20:21] offset:992
	global_load_dword v204, v98, s[20:21] offset:992
	global_load_dword v205, v94, s[20:21] offset:868
	global_load_dword v206, v92, s[20:21] offset:992
	global_load_dword v207, v99, s[20:21] offset:1116
	global_load_dword v208, v96, s[20:21] offset:1116
	global_load_dword v209, v98, s[20:21] offset:1116
	global_load_dword v210, v94, s[20:21] offset:1116
	global_load_dword v211, v97, s[20:21] offset:1116
	global_load_dword v212, v93, s[20:21] offset:1116
	global_load_dword v213, v96, s[20:21] offset:992
	global_load_dword v226, v95, s[20:21] offset:1116
	global_load_dword v227, v92, s[20:21] offset:1116
	global_load_dword v228, v94, s[20:21] offset:992
	global_load_dword v229, v99, s[20:21] offset:1240
	global_load_dword v230, v96, s[20:21] offset:1240
	global_load_dword v231, v98, s[20:21] offset:1240
	global_load_dword v232, v94, s[20:21] offset:1240
	global_load_dword v233, v99, s[20:21] offset:992
	global_load_dword v234, v97, s[20:21] offset:1240
	global_load_dword v235, v93, s[20:21] offset:1240
	global_load_dword v236, v95, s[20:21] offset:1240
	global_load_dword v237, v92, s[20:21] offset:1240
	v_mad_u32_u24 v4, v0, s59, v117
	ds_read_b128 v[0:3], v4
	ds_read_b128 v[4:7], v4 offset:64
	s_waitcnt vmcnt(33) lgkmcnt(1)
	v_mfma_f32_16x16x32_bf16 v[0:3], v[0:3], v[20:23], 0
	s_waitcnt vmcnt(32) lgkmcnt(0)
	v_mfma_f32_16x16x32_bf16 v[28:31], v[4:7], v[24:27], v[0:3]
	s_nop 5
	v_or_b32_e32 v0, s35, v119
	v_mad_u32_u24 v4, v0, s59, v117
	ds_read_b128 v[0:3], v4
	ds_read_b128 v[4:7], v4 offset:64
	s_waitcnt lgkmcnt(1)
	v_mfma_f32_16x16x32_bf16 v[0:3], v[0:3], v[20:23], 0
	s_waitcnt lgkmcnt(0)
	v_mfma_f32_16x16x32_bf16 v[32:35], v[4:7], v[24:27], v[0:3]
	s_nop 5
	v_add_u32_e32 v0, s34, v115
	v_mad_u32_u24 v4, v0, s59, v117
	ds_read_b128 v[0:3], v4
	ds_read_b128 v[4:7], v4 offset:64
	s_waitcnt lgkmcnt(1)
	v_mfma_f32_16x16x32_bf16 v[0:3], v[0:3], v[20:23], 0
	s_waitcnt lgkmcnt(0)
	v_mfma_f32_16x16x32_bf16 v[36:39], v[4:7], v[24:27], v[0:3]
	s_nop 5
	v_add_u32_e32 v0, s34, v119
	v_mad_u32_u24 v4, v0, s59, v117
	ds_read_b128 v[0:3], v4
	ds_read_b128 v[4:7], v4 offset:64
	s_waitcnt lgkmcnt(1)
	v_mfma_f32_16x16x32_bf16 v[0:3], v[0:3], v[20:23], 0
	s_waitcnt lgkmcnt(0)
	v_mfma_f32_16x16x32_bf16 v[16:19], v[4:7], v[24:27], v[0:3]
	s_nop 5
	v_or_b32_e32 v0, s33, v115
	v_mad_u32_u24 v4, v0, s59, v117
	ds_read_b128 v[0:3], v4
	ds_read_b128 v[4:7], v4 offset:64
	s_waitcnt lgkmcnt(1)
	v_mfma_f32_16x16x32_bf16 v[0:3], v[0:3], v[20:23], 0
	s_waitcnt lgkmcnt(0)
	v_mfma_f32_16x16x32_bf16 v[12:15], v[4:7], v[24:27], v[0:3]
	s_nop 5
	v_add_u32_e32 v0, s33, v119
	v_mad_u32_u24 v4, v0, s59, v117
	ds_read_b128 v[0:3], v4
	ds_read_b128 v[4:7], v4 offset:64
	s_waitcnt lgkmcnt(1)
	v_mfma_f32_16x16x32_bf16 v[0:3], v[0:3], v[20:23], 0
	s_waitcnt lgkmcnt(0)
	v_mfma_f32_16x16x32_bf16 v[8:11], v[4:7], v[24:27], v[0:3]
	s_nop 5
	v_add_u32_e32 v0, s26, v115
	v_mad_u32_u24 v4, v0, s59, v117
	ds_read_b128 v[0:3], v4
	ds_read_b128 v[4:7], v4 offset:64
	s_waitcnt lgkmcnt(1)
	v_mfma_f32_16x16x32_bf16 v[0:3], v[0:3], v[20:23], 0
	s_waitcnt lgkmcnt(0)
	v_mfma_f32_16x16x32_bf16 v[4:7], v[4:7], v[24:27], v[0:3]
	s_nop 5
	v_add_u32_e32 v0, s26, v119
	v_mad_u32_u24 v40, v0, s59, v117
	ds_read_b128 v[0:3], v40
	ds_read_b128 v[40:43], v40 offset:64
	s_waitcnt lgkmcnt(1)
	v_mfma_f32_16x16x32_bf16 v[0:3], v[0:3], v[20:23], 0
	s_waitcnt lgkmcnt(0)
	v_mfma_f32_16x16x32_bf16 v[0:3], v[40:43], v[24:27], v[0:3]
	s_waitcnt vmcnt(0)
	v_fmamk_f32 v24, v196, 0x3fb8aa3b, v32
	v_cndmask_b32_e64 v24, v220, v24, s[46:47]
	v_fmamk_f32 v16, v200, 0x3fb8aa3b, v16
	v_fmamk_f32 v26, v197, 0x3fb8aa3b, v34
	v_cndmask_b32_e64 v27, v220, v26, s[50:51]
	v_cndmask_b32_e64 v16, v220, v16, s[46:47]
	v_fmamk_f32 v17, v201, 0x3fb8aa3b, v17
	v_fmamk_f32 v22, v194, 0x3fb8aa3b, v30
	v_cndmask_b32_e64 v23, v220, v22, s[42:43]
	v_cndmask_b32_e64 v17, v220, v17, s[48:49]
	v_fmamk_f32 v18, v203, 0x3fb8aa3b, v18
	v_cndmask_b32_e64 v32, v220, v18, s[50:51]
	v_fmac_f32_e32 v35, 0x3fb8aa3b, v202
	v_fmamk_f32 v25, v198, 0x3fb8aa3b, v33
	v_cndmask_b32_e64 v26, v220, v35, s[52:53]
	v_cndmask_b32_e64 v25, v220, v25, s[48:49]
	v_max_f32_e32 v33, v27, v26
	v_max3_f32 v33, v24, v25, v33
	v_fmac_f32_e32 v19, 0x3fb8aa3b, v206
	v_cndmask_b32_e64 v18, v220, v19, s[52:53]
	v_max_f32_e32 v34, v32, v18
	v_max3_f32 v34, v16, v17, v34
	v_fmamk_f32 v12, v207, 0x3fb8aa3b, v12
	v_cndmask_b32_e64 v12, v220, v12, s[38:39]
	v_fmamk_f32 v13, v208, 0x3fb8aa3b, v13
	v_cndmask_b32_e64 v13, v220, v13, s[40:41]
	v_fmamk_f32 v14, v209, 0x3fb8aa3b, v14
	v_cndmask_b32_e64 v19, v220, v14, s[42:43]
	v_fmamk_f32 v30, v204, 0x3fb8aa3b, v38
	v_fmac_f32_e32 v15, 0x3fb8aa3b, v210
	v_cndmask_b32_e64 v14, v220, v15, s[44:45]
	v_fmamk_f32 v8, v211, 0x3fb8aa3b, v8
	v_fmamk_f32 v21, v199, 0x3fb8aa3b, v29
	v_cndmask_b32_e64 v21, v220, v21, s[40:41]
	v_cndmask_b32_e64 v8, v220, v8, s[46:47]
	v_fmamk_f32 v9, v212, 0x3fb8aa3b, v9
	v_cndmask_b32_e64 v9, v220, v9, s[48:49]
	v_fmamk_f32 v10, v226, 0x3fb8aa3b, v10
	v_cndmask_b32_e64 v15, v220, v10, s[50:51]
	v_fmac_f32_e32 v31, 0x3fb8aa3b, v205
	v_cndmask_b32_e64 v22, v220, v31, s[44:45]
	v_cndmask_b32_e64 v31, v220, v30, s[42:43]
	v_fmac_f32_e32 v11, 0x3fb8aa3b, v227
	v_cndmask_b32_e64 v10, v220, v11, s[52:53]
	v_fmamk_f32 v4, v229, 0x3fb8aa3b, v4
	v_cndmask_b32_e64 v4, v220, v4, s[38:39]
	v_fmamk_f32 v5, v230, 0x3fb8aa3b, v5
	v_cndmask_b32_e64 v5, v220, v5, s[40:41]
	v_fmamk_f32 v6, v231, 0x3fb8aa3b, v6
	v_fmamk_f32 v20, v195, 0x3fb8aa3b, v28
	v_cndmask_b32_e64 v20, v220, v20, s[38:39]
	v_cndmask_b32_e64 v6, v220, v6, s[42:43]
	v_fmac_f32_e32 v7, 0x3fb8aa3b, v232
	v_cndmask_b32_e64 v7, v220, v7, s[44:45]
	v_fmamk_f32 v0, v234, 0x3fb8aa3b, v0
	v_fmamk_f32 v29, v213, 0x3fb8aa3b, v37
	v_cndmask_b32_e64 v29, v220, v29, s[40:41]
	v_cndmask_b32_e64 v0, v220, v0, s[46:47]
	v_fmamk_f32 v1, v235, 0x3fb8aa3b, v1
	v_fmamk_f32 v28, v233, 0x3fb8aa3b, v36
	v_cndmask_b32_e64 v28, v220, v28, s[38:39]
	v_cndmask_b32_e64 v1, v220, v1, s[48:49]
	v_fmamk_f32 v2, v236, 0x3fb8aa3b, v2
	v_fmac_f32_e32 v39, 0x3fb8aa3b, v228
	v_cndmask_b32_e64 v30, v220, v39, s[44:45]
	s_mov_b32 s20, 0xf149f2ca
	v_cndmask_b32_e64 v2, v220, v2, s[50:51]
	v_fmac_f32_e32 v3, 0x3fb8aa3b, v237
	v_max_f32_e32 v11, v23, v22
	v_max3_f32 v11, v20, v21, v11
	v_max3_f32 v11, v11, s20, v33
	v_max_f32_e32 v33, v31, v30
	v_max3_f32 v33, v28, v29, v33
	v_max3_f32 v11, v11, v33, v34
	v_max_f32_e32 v33, v19, v14
	v_max_f32_e32 v34, v15, v10
	v_cndmask_b32_e64 v3, v220, v3, s[52:53]
	v_max3_f32 v33, v12, v13, v33
	v_max3_f32 v34, v8, v9, v34
	v_max3_f32 v11, v11, v33, v34
	v_max_f32_e32 v33, v6, v7
	v_max_f32_e32 v34, v2, v3
	v_max3_f32 v33, v4, v5, v33
	v_max3_f32 v34, v0, v1, v34
	v_max3_f32 v11, v11, v33, v34
	v_and_b32_e32 v34, 64, v219
	v_xor_b32_e32 v33, 16, v219
	v_add_u32_e32 v34, 64, v34
	v_cmp_lt_i32_e32 vcc, v33, v34
	s_nop 1
	v_cndmask_b32_e32 v33, v219, v33, vcc
	v_lshlrev_b32_e32 v145, 2, v33
	ds_bpermute_b32 v33, v145, v11
	s_waitcnt lgkmcnt(0)
	v_max_f32_e32 v33, v33, v33
	v_max_f32_e32 v11, v11, v33
	v_xor_b32_e32 v33, 32, v219
	v_cmp_lt_i32_e32 vcc, v33, v34
	s_nop 1
	v_cndmask_b32_e32 v33, v219, v33, vcc
	v_lshlrev_b32_e32 v149, 2, v33
	ds_bpermute_b32 v33, v149, v11
	s_waitcnt lgkmcnt(0)
	v_max3_f32 v146, v11, v33, s20
	v_sub_f32_e32 v20, v20, v146
	v_exp_f32_e32 v33, v20
	v_sub_f32_e32 v21, v21, v146
	v_exp_f32_e32 v34, v21
	v_sub_f32_e32 v21, v23, v146
	v_exp_f32_e32 v35, v21
	v_sub_f32_e32 v21, v22, v146
	v_exp_f32_e32 v36, v21
	v_sub_f32_e32 v21, v24, v146
	v_add_f32_e32 v20, 0, v33
	v_exp_f32_e32 v24, v21
	v_sub_f32_e32 v21, v25, v146
	v_add_f32_e32 v20, v34, v20
	v_exp_f32_e32 v25, v21
	v_sub_f32_e32 v21, v27, v146
	v_add_f32_e32 v20, v35, v20
	v_exp_f32_e32 v27, v21
	v_sub_f32_e32 v21, v26, v146
	v_add_f32_e32 v20, v36, v20
	v_exp_f32_e32 v26, v21
	v_sub_f32_e32 v21, v28, v146
	v_add_f32_e32 v20, v24, v20
	v_exp_f32_e32 v28, v21
	v_sub_f32_e32 v21, v29, v146
	v_add_f32_e32 v20, v25, v20
	v_exp_f32_e32 v29, v21
	v_sub_f32_e32 v21, v31, v146
	v_add_f32_e32 v20, v27, v20
	v_exp_f32_e32 v31, v21
	v_sub_f32_e32 v21, v30, v146
	v_add_f32_e32 v20, v26, v20
	v_exp_f32_e32 v30, v21
	v_sub_f32_e32 v16, v16, v146
	v_add_f32_e32 v20, v28, v20
	v_exp_f32_e32 v37, v16
	v_sub_f32_e32 v17, v17, v146
	v_add_f32_e32 v20, v29, v20
	v_exp_f32_e32 v38, v17
	v_sub_f32_e32 v17, v32, v146
	v_add_f32_e32 v20, v31, v20
	v_exp_f32_e32 v32, v17
	v_sub_f32_e32 v17, v18, v146
	v_add_f32_e32 v20, v30, v20
	v_exp_f32_e32 v39, v17
	v_sub_f32_e32 v12, v12, v146
	v_add_f32_e32 v16, v37, v20
	v_exp_f32_e32 v40, v12
	v_sub_f32_e32 v13, v13, v146
	v_add_f32_e32 v16, v38, v16
	v_exp_f32_e32 v41, v13
	v_sub_f32_e32 v13, v19, v146
	v_add_f32_e32 v16, v32, v16
	v_exp_f32_e32 v42, v13
	v_sub_f32_e32 v13, v14, v146
	v_add_f32_e32 v16, v39, v16
	v_exp_f32_e32 v43, v13
	v_sub_f32_e32 v8, v8, v146
	v_add_f32_e32 v12, v40, v16
	v_exp_f32_e32 v44, v8
	v_sub_f32_e32 v9, v9, v146
	v_add_f32_e32 v12, v41, v12
	v_exp_f32_e32 v45, v9
	v_sub_f32_e32 v9, v15, v146
	v_add_f32_e32 v12, v42, v12
	v_exp_f32_e32 v46, v9
	v_sub_f32_e32 v9, v10, v146
	v_add_f32_e32 v12, v43, v12
	v_exp_f32_e32 v47, v9
	v_sub_f32_e32 v4, v4, v146
	v_add_f32_e32 v8, v44, v12
	v_exp_f32_e32 v48, v4
	v_sub_f32_e32 v5, v5, v146
	v_add_f32_e32 v8, v45, v8
	v_exp_f32_e32 v49, v5
	v_sub_f32_e32 v5, v6, v146
	v_add_f32_e32 v8, v46, v8
	v_exp_f32_e32 v50, v5
	v_sub_f32_e32 v5, v7, v146
	v_add_f32_e32 v8, v47, v8
	v_exp_f32_e32 v51, v5
	v_sub_f32_e32 v0, v0, v146
	v_add_f32_e32 v4, v48, v8
	v_exp_f32_e32 v52, v0
	v_sub_f32_e32 v1, v1, v146
	v_add_f32_e32 v4, v49, v4
	v_exp_f32_e32 v53, v1
	v_sub_f32_e32 v1, v2, v146
	v_add_f32_e32 v4, v50, v4
	v_exp_f32_e32 v54, v1
	v_sub_f32_e32 v1, v3, v146
	v_add_f32_e32 v4, v51, v4
	v_exp_f32_e32 v55, v1
	v_add_f32_e32 v0, v52, v4
	v_add_f32_e32 v0, v53, v0
	v_add_f32_e32 v0, v54, v0
	v_add_f32_e32 v0, v55, v0
	v_sub_f32_e32 v11, 0xf149f2ca, v146
	ds_bpermute_b32 v2, v145, v0
	v_exp_f32_e32 v1, v11
	s_or_b32 s20, s35, s60
	v_lshl_add_u32 v16, s20, 1, v121
	v_add_u32_e32 v12, v16, v123
	s_waitcnt lgkmcnt(0)
	v_add_f32_e32 v90, v0, v2
	v_mul_f32_e32 v20, 0, v1
	v_cvt_pk_bf16_f32 v0, v33, v34
	v_cvt_pk_bf16_f32 v1, v35, v36
	v_cvt_pk_bf16_f32 v2, v24, v25
	v_cvt_pk_bf16_f32 v3, v27, v26
	ds_read2_b64 v[4:7], v12 offset1:4
	v_add_u32_e32 v8, 0x4000, v12
	v_add_u32_e32 v12, 0x8000, v12
	v_add_u32_e32 v16, v16, v125
	ds_read2_b64 v[8:11], v8 offset0:32 offset1:36
	ds_read2_b64 v[12:15], v12 offset0:64 offset1:68
	ds_read2_b64 v[16:19], v16 offset1:4
	v_mov_b32_e32 v21, v20
	v_mov_b32_e32 v22, v20
	v_mov_b32_e32 v23, v20
	s_or_b32 s20, s34, s60
	ds_bpermute_b32 v91, v149, v90
	s_waitcnt lgkmcnt(4)
	v_mfma_f32_16x16x32_bf16 v[4:7], v[4:7], v[0:3], v[20:23]
	s_waitcnt lgkmcnt(3)
	v_mfma_f32_16x16x32_bf16 v[8:11], v[8:11], v[0:3], v[20:23]
	s_waitcnt lgkmcnt(2)
	v_mfma_f32_16x16x32_bf16 v[12:15], v[12:15], v[0:3], v[20:23]
	s_waitcnt lgkmcnt(1)
	v_mfma_f32_16x16x32_bf16 v[0:3], v[16:19], v[0:3], v[20:23]
	v_cvt_pk_bf16_f32 v16, v28, v29
	v_cvt_pk_bf16_f32 v17, v31, v30
	v_cvt_pk_bf16_f32 v18, v37, v38
	v_cvt_pk_bf16_f32 v19, v32, v39
	s_nop 2
	v_lshl_add_u32 v21, s20, 1, v121
	v_add_u32_e32 v26, v21, v123
	ds_read2_b64 v[22:25], v26 offset1:4
	s_waitcnt lgkmcnt(0)
	v_mfma_f32_16x16x32_bf16 v[4:7], v[22:25], v[16:19], v[4:7]
	v_add_u32_e32 v22, 0x4000, v26
	ds_read2_b64 v[22:25], v22 offset0:32 offset1:36
	v_add_u32_e32 v21, v21, v125
	s_waitcnt lgkmcnt(0)
	v_mfma_f32_16x16x32_bf16 v[8:11], v[22:25], v[16:19], v[8:11]
	v_add_u32_e32 v22, 0x8000, v26
	ds_read2_b64 v[22:25], v22 offset0:64 offset1:68
	s_or_b32 s20, s33, s60
	s_waitcnt lgkmcnt(0)
	v_mfma_f32_16x16x32_bf16 v[12:15], v[22:25], v[16:19], v[12:15]
	ds_read2_b64 v[22:25], v21 offset1:4
	v_lshl_add_u32 v21, s20, 1, v121
	v_add_u32_e32 v26, v21, v123
	s_waitcnt lgkmcnt(0)
	v_mfma_f32_16x16x32_bf16 v[0:3], v[22:25], v[16:19], v[0:3]
	v_cvt_pk_bf16_f32 v16, v40, v41
	v_cvt_pk_bf16_f32 v17, v42, v43
	v_cvt_pk_bf16_f32 v18, v44, v45
	v_cvt_pk_bf16_f32 v19, v46, v47
	ds_read2_b64 v[22:25], v26 offset1:4
	s_waitcnt lgkmcnt(0)
	v_mfma_f32_16x16x32_bf16 v[4:7], v[22:25], v[16:19], v[4:7]
	v_add_u32_e32 v22, 0x4000, v26
	ds_read2_b64 v[22:25], v22 offset0:32 offset1:36
	v_add_u32_e32 v21, v21, v125
	s_waitcnt lgkmcnt(0)
	v_mfma_f32_16x16x32_bf16 v[8:11], v[22:25], v[16:19], v[8:11]
	v_add_u32_e32 v22, 0x8000, v26
	ds_read2_b64 v[22:25], v22 offset0:64 offset1:68
	s_or_b32 s20, s26, s60
	s_waitcnt lgkmcnt(0)
	v_mfma_f32_16x16x32_bf16 v[12:15], v[22:25], v[16:19], v[12:15]
	ds_read2_b64 v[22:25], v21 offset1:4
	v_lshl_add_u32 v21, s20, 1, v121
	v_add_u32_e32 v26, v21, v123
	s_waitcnt lgkmcnt(0)
	v_mfma_f32_16x16x32_bf16 v[0:3], v[22:25], v[16:19], v[0:3]
	v_cvt_pk_bf16_f32 v16, v48, v49
	v_cvt_pk_bf16_f32 v17, v50, v51
	v_cvt_pk_bf16_f32 v18, v52, v53
	v_cvt_pk_bf16_f32 v19, v54, v55
	ds_read2_b64 v[22:25], v26 offset1:4
	s_waitcnt lgkmcnt(0)
	v_mfma_f32_16x16x32_bf16 v[4:7], v[22:25], v[16:19], v[4:7]
	v_add_u32_e32 v22, 0x4000, v26
	ds_read2_b64 v[22:25], v22 offset0:32 offset1:36
	v_add_u32_e32 v21, v21, v125
	s_waitcnt lgkmcnt(0)
	v_mfma_f32_16x16x32_bf16 v[8:11], v[22:25], v[16:19], v[8:11]
	v_add_u32_e32 v22, 0x8000, v26
	ds_read2_b64 v[22:25], v22 offset0:64 offset1:68
	s_or_b32 s20, s22, 1
	s_waitcnt lgkmcnt(0)
	v_mfma_f32_16x16x32_bf16 v[12:15], v[22:25], v[16:19], v[12:15]
	ds_read2_b64 v[22:25], v21 offset1:4
	s_waitcnt lgkmcnt(0)
	v_mfma_f32_16x16x32_bf16 v[16:19], v[22:25], v[16:19], v[0:3]
	s_nop 2
	v_sub_u32_e64 v0, s20, 4 clamp
	s_nop 0
	v_readfirstlane_b32 s21, v0
	s_min_u32 s21, s21, 8
	v_sub_u32_e64 v0, s20, 5 clamp
	v_cmp_ne_u32_e32 vcc, s21, v0
	v_lshl_or_b32 v0, s20, 6, v111
	v_or_b32_e32 v0, s2, v0
	v_mov_b32_e32 v1, s3
	v_lshlrev_b64 v[0:1], 11, v[0:1]
	v_lshl_add_u64 v[22:23], v[142:143], 0, v[0:1]
	global_load_dwordx4 v[0:3], v[22:23], off
	global_load_dwordx4 v[50:53], v[22:23], off offset:64
	s_cbranch_vccz .LBB0_120

	s_lshl_b32 s26, s21, 6
	s_add_i32 s33, s26, 0x1c0
	v_add_u32_e32 v194, s33, v108
	v_ashrrev_i32_e32 v195, 31, v194
	v_lshlrev_b64 v[194:195], 11, v[194:195]
	s_lshl_b32 s26, s21, 7
	v_lshl_add_u64 v[194:195], v[70:71], 0, v[194:195]
	v_lshl_add_u64 v[198:199], v[68:69], 0, s[26:27]
	s_barrier
	global_load_dwordx4 v[194:197], v[194:195], off
	s_nop 0
	global_load_dwordx4 v[198:201], v[198:199], off offset:896
	s_and_b32 s26, s33, 0x1c0
	v_add_u32_e32 v202, s26, v108
	v_mad_u64_u32 v[204:205], s[34:35], v202, s59, v[110:111]
	v_lshl_add_u32 v206, s26, 1, v109
	s_waitcnt vmcnt(1)
	ds_write_b128 v204, v[194:197]
	s_waitcnt vmcnt(0)
	ds_write_b128 v206, v[198:201]
	s_waitcnt lgkmcnt(0)
	s_barrier

.LBB0_631:
	v_lshl_or_b32 v245, s0, 7, v211
	v_lshlrev_b32_e32 v245, 2, v245
	global_load_dwordx4 v[64:67], v245, s[22:23] offset:16
	global_load_dwordx4 v[84:87], v245, s[22:23]
	global_load_dwordx4 v[68:71], v245, s[48:49] offset:16
	global_load_dwordx4 v[88:91], v245, s[48:49]
	global_load_dwordx4 v[72:75], v245, s[50:51] offset:16
	global_load_dwordx4 v[92:95], v245, s[50:51]
	global_load_dwordx4 v[60:63], v245, s[46:47] offset:16
	global_load_dwordx4 v[80:83], v245, s[46:47]
	v_cmp_lt_i32_e32 vcc, 14, v193
	s_mov_b64 s[62:63], 0
	s_and_saveexec_b64 s[2:3], vcc
	s_xor_b64 s[2:3], exec, s[2:3]

	s_mov_b64 s[62:63], exec
	ds_write_b128 v213, v[110:113]

	s_or_saveexec_b64 s[44:45], s[2:3]
	v_mov_b64_e32 v[240:241], v[98:99]
	v_mov_b32_e32 v244, v213
	v_mov_b64_e32 v[242:243], v[100:101]
	s_xor_b64 exec, exec, s[44:45]
	s_cbranch_execz .LBB0_637

	v_cmp_eq_u32_e32 vcc, 0, v193
	s_mov_b64 s[2:3], s[62:63]
	s_and_saveexec_b64 s[38:39], vcc

	s_or_b64 s[2:3], s[62:63], exec
	ds_write_b128 v212, v[150:153]

	s_or_b64 exec, exec, s[38:39]
	s_andn2_b64 s[38:39], s[62:63], exec
	s_and_b64 s[2:3], s[2:3], exec
	v_mov_b64_e32 v[240:241], v[130:131]
	s_or_b64 s[62:63], s[38:39], s[2:3]
	v_mov_b32_e32 v244, v212
	v_mov_b64_e32 v[242:243], v[132:133]
.LBB0_637:
	s_or_b64 exec, exec, s[44:45]
	s_and_saveexec_b64 s[44:45], s[62:63]
	s_cbranch_execz .LBB0_646

	v_cmp_lt_i32_e32 vcc, 14, v193
	s_mov_b64 s[62:63], 0
	ds_write_b128 v244, v[240:243] offset:16
	s_and_saveexec_b64 s[2:3], vcc
	s_xor_b64 s[2:3], exec, s[2:3]

	s_mov_b64 s[62:63], exec
	ds_write_b128 v226, v[12:15]

	s_or_saveexec_b64 s[2:3], s[2:3]
	v_mov_b64_e32 v[242:243], v[6:7]
	v_mov_b32_e32 v244, v226
	v_mov_b64_e32 v[240:241], v[4:5]
	s_xor_b64 exec, exec, s[2:3]
	s_cbranch_execz .LBB0_644

	v_cmp_eq_u32_e32 vcc, 0, v193
	s_mov_b64 s[38:39], s[62:63]
	s_and_saveexec_b64 s[40:41], vcc

	s_or_b64 s[38:39], s[62:63], exec
	ds_write_b128 v227, v[52:55]

	s_or_b64 exec, exec, s[40:41]
	s_andn2_b64 s[40:41], s[62:63], exec
	s_and_b64 s[38:39], s[38:39], exec
	v_mov_b64_e32 v[242:243], v[38:39]
	s_or_b64 s[62:63], s[40:41], s[38:39]
	v_mov_b32_e32 v244, v227
	v_mov_b64_e32 v[240:241], v[36:37]
.LBB0_644:
	s_or_b64 exec, exec, s[2:3]
	s_and_b64 exec, exec, s[62:63]

	ds_write_b128 v244, v[240:243] offset:16
.LBB0_646:
	s_or_b64 exec, exec, s[44:45]
	v_lshl_or_b32 v208, s0, 7, v211
	s_mov_b64 s[0:1], -1
	s_cmp_gt_i32 s92, 31
	v_ashrrev_i32_e32 v209, 31, v208
	s_cbranch_scc1 .LBB0_648

	s_mov_b64 s[0:1], 0
.LBB0_648:
	s_andn2_b64 vcc, exec, s[0:1]
	s_cbranch_vccnz .LBB0_656

	s_sub_i32 s0, s92, 32
	s_mul_hi_u32 s1, s0, 0x10800
	s_mul_i32 s0, s0, 0x10800
	v_readlane_b32 s2, v253, 10
	s_add_u32 s0, s2, s0
	v_readlane_b32 s2, v253, 11
	s_addc_u32 s1, s2, s1
	v_lshl_add_u64 v[240:241], v[208:209], 2, s[0:1]
	v_lshlrev_b32_e32 v178, 2, v202
	s_mov_b64 s[0:1], exec
	v_readlane_b32 s2, v255, 10
	v_readlane_b32 s3, v255, 11
	s_and_b64 s[2:3], s[0:1], s[2:3]
	s_mov_b64 exec, s[2:3]
	s_cbranch_execz .LBB0_652

	v_readlane_b32 s2, v255, 20
	v_lshl_add_u64 v[242:243], v[240:241], 0, v[178:179]
	v_readlane_b32 s3, v255, 21
	global_store_dwordx4 v[242:243], v[150:153], off
	global_store_dwordx4 v[242:243], v[130:133], off offset:16
	s_and_b64 exec, exec, s[2:3]
	s_cbranch_execz .LBB0_652

	v_add_co_u32_e32 v242, vcc, 0x5000, v240
	s_nop 1
	v_addc_co_u32_e32 v243, vcc, 0, v241, vcc
	global_store_dwordx4 v[242:243], v[166:169], off offset:2048
	global_store_dwordx4 v[242:243], v[154:157], off offset:2064
.LBB0_652:
	s_or_b64 exec, exec, s[0:1]
	s_mov_b64 s[0:1], exec
	v_readlane_b32 s2, v255, 14
	v_readlane_b32 s3, v255, 15
	s_and_b64 s[2:3], s[0:1], s[2:3]
	s_mov_b64 exec, s[2:3]
	s_cbranch_execz .LBB0_655

	v_lshl_add_u64 v[242:243], v[240:241], 0, v[178:179]
	v_add_co_u32_e32 v242, vcc, 0xfffe2000, v242
	v_readlane_b32 s2, v255, 22
	s_nop 0
	v_addc_co_u32_e32 v243, vcc, -1, v243, vcc
	v_readlane_b32 s3, v255, 23
	global_store_dwordx4 v[242:243], v[12:15], off offset:-1024
	global_store_dwordx4 v[242:243], v[4:7], off offset:-1008
	s_and_b64 exec, exec, s[2:3]
	s_cbranch_execz .LBB0_655

	v_add_co_u32_e32 v240, vcc, 0xd000, v240
	s_nop 1
	v_addc_co_u32_e32 v241, vcc, 0, v241, vcc
	global_store_dwordx4 v[240:241], v[8:11], off offset:3072
	global_store_dwordx4 v[240:241], v[0:3], off offset:3088

.LBB0_656:
	s_waitcnt lgkmcnt(0)
	s_barrier
	s_and_b64 vcc, exec, s[82:83]
	s_cbranch_vccz .Lgm_z_t0
	ds_read_b128 v[170:173], v228
	ds_read_b128 v[174:177], v228 offset:16
	s_branch .Lgm_l_t0
